# phase_cbias pe staging: skipped by workgroups with no cbias item; 8 loads in flight for the 16 that have one
# speedup vs baseline: 1.0618x; 1.0022x over previous
.LBB0_75:
	s_or_b64 exec, exec, s[4:5]
	v_mov_b32_e32 v0, s1
	v_mov_b32_e32 v1, s0
	v_mov_b32_e32 v6, v192
	v_readfirstlane_b32 s10, v1
	v_readfirstlane_b32 s11, v0
	v_mov_b32_e32 v0, s30
	v_mov_b32_e32 v1, s31
	v_readlane_b32 s0, v252, 2
	v_readlane_b32 s1, v252, 3
	v_readfirstlane_b32 s20, v0
	v_add_u32_e32 v4, s0, v6
	v_readfirstlane_b32 s21, v1
	v_readlane_b32 s12, v252, 7
	v_readlane_b32 s13, v252, 8
	s_nop 0
	s_andn2_b64 vcc, exec, s[12:13]
	s_cbranch_vccnz .LBB0_87
	v_cmp_gt_i32_e32 vcc, s74, v4
	s_barrier
	s_and_saveexec_b64 s[0:1], vcc
	s_mov_b64 s[14:15], 0x800
	s_cbranch_execz .LBB0_78
	global_load_dwordx2 v[0:1], v231, s[10:11] offset:168
	v_readlane_b32 s4, v253, 13
	v_ashrrev_i32_e32 v5, 31, v4
	s_nop 0
	v_lshl_add_u32 v7, v6, 2, s4
	s_lshl_b64 s[4:5], s[58:59], 14
	v_lshl_add_u64 v[2:3], v[4:5], 2, s[4:5]
	s_waitcnt vmcnt(0)
	v_readfirstlane_b32 s12, v0
	v_readfirstlane_b32 s13, v1
	s_nop 1
	v_lshl_add_u64 v[10:11], s[12:13], 0, v[2:3]
	global_load_dword v12, v[10:11], off
	global_load_dword v13, v[10:11], off offset:2048
	v_add_co_u32_e32 v10, vcc, 0x1000, v10
	s_nop 1
	v_addc_co_u32_e32 v11, vcc, 0, v11, vcc
	global_load_dword v14, v[10:11], off
	global_load_dword v15, v[10:11], off offset:2048
	v_add_co_u32_e32 v10, vcc, 0x1000, v10
	s_nop 1
	v_addc_co_u32_e32 v11, vcc, 0, v11, vcc
	global_load_dword v16, v[10:11], off
	global_load_dword v17, v[10:11], off offset:2048
	v_add_co_u32_e32 v10, vcc, 0x1000, v10
	s_nop 1
	v_addc_co_u32_e32 v11, vcc, 0, v11, vcc
	global_load_dword v18, v[10:11], off
	global_load_dword v19, v[10:11], off offset:2048
	s_waitcnt vmcnt(0)
	ds_write_b32 v7, v12
	ds_write_b32 v7, v13 offset:2048
	ds_write_b32 v7, v14 offset:4096
	ds_write_b32 v7, v15 offset:6144
	ds_write_b32 v7, v16 offset:8192
	ds_write_b32 v7, v17 offset:10240
	ds_write_b32 v7, v18 offset:12288
	ds_write_b32 v7, v19 offset:14336
